# PEER table conversion split 31/1 (latent-chain workgroups convert only one item each now that conversion is cheap)
# speedup vs baseline: 1.0075x; 1.0075x over previous
.LBB0_226:
	v_readlane_b32 s4, v253, 0
	s_and_b32 s33, s4, 7
	s_mov_b64 s[6:7], s[80:81]
	s_xor_b32 s2, s33, 7
	s_add_i32 s2, s6, s2
	s_lshr_b32 s83, s2, 3
	s_cmpk_lt_u32 s4, 0xf00
	s_cselect_b64 s[2:3], -1, 0
	v_readlane_b32 s5, v253, 1
	v_writelane_b32 v253, s2, 22
	s_mul_i32 s1, s7, s6
	s_mul_i32 s97, s1, s0
	v_writelane_b32 v253, s3, 23
	s_lshr_b32 s2, s4, 3
	v_writelane_b32 v253, s2, 24
	s_lshl_b32 s2, s33, 7
	s_add_u32 s0, s68, 0x38e00200
	v_writelane_b32 v253, s2, 25
	s_addc_u32 s1, s69, 0
	v_writelane_b32 v253, s0, 26
	v_lshrrev_b32_e32 v1, 20, v0
	v_lshrrev_b32_e32 v0, 10, v0
	v_writelane_b32 v253, s1, 27
	s_add_u32 s0, s68, 0x38e00400
	s_addc_u32 s1, s69, 0
	v_writelane_b32 v253, s0, 18
	v_or_b32_e32 v0, v0, v1
	s_mov_b32 s81, 0
	v_writelane_b32 v253, s1, 19
	s_add_u32 s0, s68, 0x38e00500
	s_addc_u32 s1, s69, 0
	v_writelane_b32 v253, s0, 10
	s_mov_b32 s7, s81
	s_mov_b32 s30, 2
	v_writelane_b32 v253, s1, 11
	s_add_u32 s0, s68, 0x38e00600
	s_addc_u32 s1, s69, 0
	v_writelane_b32 v253, s0, 12
	s_movk_i32 s89, 0xff00
	s_movk_i32 s91, 0xff
	v_writelane_b32 v253, s1, 13
	s_add_u32 s0, s68, 0x38e00700
	s_addc_u32 s1, s69, 0
	v_writelane_b32 v253, s0, 14
	v_mov_b32_e32 v129, 0
	s_mov_b64 s[40:41], 0
	v_writelane_b32 v253, s1, 15
	s_add_u32 s0, s68, 0x38e00800
	s_addc_u32 s1, s69, 0
	v_writelane_b32 v253, s0, 16
	s_mov_b64 s[86:87], 0x1a00080
	s_mov_b64 s[36:37], 0xa3ff000
	v_writelane_b32 v253, s1, 17
	s_add_u32 s0, s68, 0x38e00900
	s_addc_u32 s1, s69, 0
	v_writelane_b32 v253, s0, 28
	v_mov_b32_e32 v178, 0x12004
	v_mov_b32_e32 v179, 1
	v_writelane_b32 v253, s1, 29
	s_add_u32 s0, s68, 0x38e00a00
	s_addc_u32 s1, s69, 0
	v_writelane_b32 v253, s0, 30
	s_mov_b32 s88, 0x3e38aa3b
	s_movk_i32 s10, 0x1f8
	v_writelane_b32 v253, s1, 31
	s_add_u32 s0, s68, 0x38e00b00
	s_addc_u32 s1, s69, 0
	v_writelane_b32 v253, s0, 32
	s_brev_b32 s11, -2
	s_brev_b32 s12, 18
	v_writelane_b32 v253, s1, 33
	s_add_u32 s0, s68, 0x38e00c00
	s_addc_u32 s1, s69, 0
	v_writelane_b32 v253, s0, 34
	s_mov_b32 s13, 0x800000
	s_brev_b32 s14, 1
	v_writelane_b32 v253, s1, 35
	s_add_u32 s0, s68, 0x38e00d00
	s_addc_u32 s1, s69, 0
	v_writelane_b32 v253, s0, 36
	v_mov_b32_e32 v180, 0x3c0881c4
	v_mov_b32_e32 v181, 0xbab64f3b
	v_writelane_b32 v253, s1, 37
	s_add_u32 s0, s68, 0x38e00e00
	s_addc_u32 s1, s69, 0
	v_writelane_b32 v253, s0, 38
	s_mov_b32 s15, 0x3e800000
	s_mov_b32 s16, 0x3f400000
	v_writelane_b32 v253, s1, 39
	s_add_u32 s0, s68, 0x38e00f00
	s_addc_u32 s1, s69, 0
	v_writelane_b32 v253, s0, 40
	s_mov_b32 s17, 0x3fa00000
	s_mov_b32 s18, 0x3fe00000
	v_writelane_b32 v253, s1, 41
	s_add_u32 s0, s68, 0x38e01000
	s_addc_u32 s1, s69, 0
	v_writelane_b32 v253, s0, 42
	s_mov_b32 s19, 0x40200000
	s_mov_b32 s20, 0x40600000
	v_writelane_b32 v253, s1, 43
	s_add_u32 s0, s68, 0x38e01100
	s_addc_u32 s1, s69, 0
	v_writelane_b32 v253, s0, 44
	s_mov_b32 s21, 0x40a00000
	s_movk_i32 s22, 0x1fff
	v_writelane_b32 v253, s1, 45
	s_add_u32 s0, s68, 0x38e01200
	s_addc_u32 s1, s69, 0
	v_writelane_b32 v253, s0, 46
	s_movk_i32 s23, 0x6000
	s_mov_b32 s24, 0xa000
	v_writelane_b32 v253, s1, 47
	s_add_u32 s0, s68, 0x38e01300
	s_addc_u32 s1, s69, 0
	v_writelane_b32 v253, s0, 48
	s_cmp_eq_u32 s63, 15
	s_mov_b32 s25, 0x13600000
	v_writelane_b32 v253, s1, 49
	s_cselect_b64 s[0:1], -1, 0
	v_writelane_b32 v253, s0, 50
	s_cmp_eq_u32 s63, 14
	s_mov_b32 s26, 0x9fff
	v_writelane_b32 v253, s1, 51
	s_cselect_b64 s[0:1], -1, 0
	v_writelane_b32 v253, s0, 52
	s_cmp_eq_u32 s63, 13
	v_mov_b32_e32 v182, 0x3727c5ac
	v_writelane_b32 v253, s1, 53
	s_cselect_b64 s[0:1], -1, 0
	v_writelane_b32 v253, s0, 54
	s_cmp_eq_u32 s63, 12
	s_movk_i32 s28, 0x7f
	v_writelane_b32 v253, s1, 55
	s_cselect_b64 s[0:1], -1, 0
	v_writelane_b32 v253, s0, 56
	s_cmp_eq_u32 s63, 11
	s_movk_i32 s29, 0x7f00
	v_writelane_b32 v253, s1, 57
	s_cselect_b64 s[0:1], -1, 0
	v_writelane_b32 v253, s0, 58
	s_cmp_eq_u32 s63, 10
	v_mov_b32_e32 v183, 0x7f
	v_writelane_b32 v253, s1, 59
	s_cselect_b64 s[0:1], -1, 0
	v_writelane_b32 v253, s0, 60
	s_cmp_eq_u32 s63, 9
	v_mov_b32_e32 v184, 0x7d
	v_writelane_b32 v253, s1, 61
	s_cselect_b64 s[0:1], -1, 0
	v_writelane_b32 v253, s0, 62
	s_cmp_eq_u32 s63, 8
	s_mov_b32 s82, 0x41d00000
	v_writelane_b32 v253, s1, 63
	s_cselect_b64 s[0:1], -1, 0
	v_writelane_b32 v254, s0, 0
	s_cmp_eq_u32 s63, 7
	v_mov_b32_e32 v185, 0x7b
	v_writelane_b32 v254, s1, 1
	s_cselect_b64 s[0:1], -1, 0
	v_writelane_b32 v254, s0, 2
	s_cmp_eq_u32 s63, 6
	v_mov_b32_e32 v186, 0x79
	v_writelane_b32 v254, s1, 3
	s_cselect_b64 s[0:1], -1, 0
	v_writelane_b32 v254, s0, 4
	s_cmp_eq_u32 s63, 5
	s_mov_b32 s90, 0x3d1d89d9
	v_writelane_b32 v254, s1, 5
	s_cselect_b64 s[0:1], -1, 0
	v_writelane_b32 v254, s0, 6
	s_cmp_eq_u32 s63, 4
	v_not_b32_e32 v187, 63
	v_writelane_b32 v254, s1, 7
	s_cselect_b64 s[0:1], -1, 0
	v_writelane_b32 v254, s0, 8
	s_cmp_eq_u32 s63, 3
	v_mov_b32_e32 v189, 0xf149f2ca
	v_writelane_b32 v254, s1, 9
	s_cselect_b64 s[0:1], -1, 0
	v_writelane_b32 v254, s0, 10
	s_cmp_eq_u32 s63, 2
	v_not_b32_e32 v190, 31
	v_writelane_b32 v254, s1, 11
	s_cselect_b64 s[0:1], -1, 0
	v_writelane_b32 v254, s0, 12
	s_cmp_eq_u32 s63, 1
	v_mov_b32_e32 v191, 0x7fc00000
	v_writelane_b32 v254, s1, 13
	s_cselect_b64 s[0:1], -1, 0
	v_writelane_b32 v254, s0, 14
	s_cmp_eq_u32 s63, 0
	s_nop 0
	v_writelane_b32 v254, s1, 15
	s_cselect_b64 s[0:1], -1, 0
	v_writelane_b32 v254, s0, 16
	s_nop 1
	v_writelane_b32 v254, s1, 17
	s_lshl_b32 s0, s63, 8
	s_add_u32 s0, s76, s0
	s_addc_u32 s1, s77, 0
	s_add_u32 s2, s0, 0x1400
	s_addc_u32 s3, s1, 0
	v_writelane_b32 v254, s2, 18
	s_add_u32 s0, s0, 0x2400
	s_addc_u32 s1, s1, 0
	v_writelane_b32 v254, s3, 19
	v_writelane_b32 v254, s0, 20
	s_nop 1
	v_writelane_b32 v254, s1, 21
	s_add_u32 s0, s68, 0x38e03400
	s_addc_u32 s1, s69, 0
	v_writelane_b32 v254, s0, 22
	s_nop 1
	v_writelane_b32 v254, s1, 23
	s_add_u32 s0, s68, 0x38e03500
	s_addc_u32 s1, s69, 0
	v_writelane_b32 v254, s0, 24
	s_cmpk_lt_i32 s4, 0x1400
	s_mov_b64 s[68:69], 0xb3fec00
	v_writelane_b32 v254, s1, 25
	s_movk_i32 s0, 0x3ff
	v_and_or_b32 v0, v0, s0, v133
	v_cmp_eq_u32_e64 s[0:1], 0, v0
	v_mov_b32_e32 v0, 0x100
	v_sub_co_u32_e32 v0, vcc, s4, v0
	v_writelane_b32 v254, s0, 26
	s_nop 1
	v_writelane_b32 v254, s1, 27
	s_cselect_b64 s[0:1], -1, 0
	v_writelane_b32 v254, s0, 28
	s_cmpk_lt_u32 s4, 0xa00
	s_nop 0
	v_writelane_b32 v254, s1, 29
	s_cselect_b64 s[0:1], -1, 0
	v_writelane_b32 v254, s0, 30
	s_add_i32 s2, s6, 0xffffff00
	s_nop 0
	v_writelane_b32 v254, s1, 31
	s_and_b64 s[0:1], vcc, exec
	v_writelane_b32 v254, s2, 32
	s_cselect_b32 s0, 0x100000, s2
	s_cmpk_gt_u32 s6, 0x13f
	v_readfirstlane_b32 s1, v0
	s_cselect_b32 s0, s0, s6
	s_add_i32 s98, s4, 0x1f00
	s_cmpk_lt_u32 s4, 0x100
	s_cselect_b32 s98, s98, s1
	s_cmpk_eq_u32 s6, 0x200
	s_cselect_b32 s1, s98, s1
	s_cselect_b64 s[98:99], -1, 0
	s_cmpk_lt_i32 s4, 0x500
	v_writelane_b32 v254, s1, 33
	v_writelane_b32 v254, s0, 34
	s_cselect_b64 s[0:1], -1, 0
	v_writelane_b32 v254, s0, 35
	s_cmpk_gt_u32 s6, 0x1ff
	s_nop 0
	v_writelane_b32 v254, s1, 36
	s_cselect_b64 s[0:1], -1, 0
	s_cmpk_gt_u32 s4, 0xff
	s_cselect_b64 s[2:3], -1, 0
	s_and_b64 s[0:1], s[2:3], s[0:1]
	s_cmpk_lt_i32 s4, 0x2100
	s_cselect_b64 s[2:3], -1, 0
	s_and_b64 s[0:1], s[2:3], s[0:1]
	s_lshl_b64 s[76:77], s[6:7], 8
	s_or_b64 s[0:1], s[0:1], s[98:99]
	v_writelane_b32 v254, s0, 37
	s_cmpk_lt_u32 s4, 0x1400
	v_readlane_b32 s2, v253, 20
	v_writelane_b32 v254, s1, 38
	s_cselect_b64 s[0:1], -1, 0
	v_writelane_b32 v254, s0, 39
	s_lshl_b32 s84, s6, 2
	v_readlane_b32 s3, v253, 21
	v_writelane_b32 v254, s1, 40
	s_bfe_i32 s0, s6, 0x1001d
	v_writelane_b32 v254, s0, 41
	s_abs_i32 s0, s84
	v_cvt_f32_u32_e32 v0, s0
	v_writelane_b32 v254, s0, 42
	s_sub_i32 s0, 0, s0
	s_lshl_b64 s[8:9], s[2:3], 4
	v_rcp_iflag_f32_e32 v0, v0
	s_lshl_b32 s1, s33, 18
	s_lshl_b32 s5, s4, 2
	s_mov_b64 s[34:35], s[76:77]
	v_mul_f32_e32 v0, 0x4f7ffffe, v0
	v_cvt_u32_f32_e32 v0, v0
	v_mul_lo_u32 v1, s0, v0
	v_readlane_b32 s0, v254, 33
	s_lshl_b32 s0, s0, 13
	v_writelane_b32 v254, s0, 43
	s_lshl_b32 s0, s6, 13
	s_add_i32 s0, s0, 0xffe00000
	v_writelane_b32 v254, s0, 44
	v_writelane_b32 v254, s8, 45
	s_mov_b32 s0, s6
	v_mul_hi_u32 v1, v0, v1
	v_writelane_b32 v254, s9, 46
	s_lshl_b64 s[8:9], s[6:7], 13
	v_writelane_b32 v254, s8, 47
	s_lshl_b64 s[6:7], s[6:7], 12
	s_add_u32 s2, s2, s76
	v_writelane_b32 v254, s9, 48
	v_writelane_b32 v254, s0, 49
	s_addc_u32 s3, s3, s77
	s_ashr_i32 s85, s84, 31
	v_writelane_b32 v254, s1, 50
	v_writelane_b32 v254, s6, 51
	v_add_u32_e32 v176, v0, v1
	s_add_i32 s0, s84, s5
	v_writelane_b32 v254, s7, 52
	v_writelane_b32 v254, s2, 53
	s_lshl_b64 s[6:7], s[84:85], 12
	v_writelane_b32 v253, s6, 8
	v_writelane_b32 v254, s3, 54
	v_writelane_b32 v254, s5, 55
	v_writelane_b32 v254, s0, 56
	s_lshl_b32 s2, s33, 17
	v_mbcnt_lo_u32_b32 v0, -1, 0
	s_lshl_b64 s[4:5], s[84:85], 11
	v_writelane_b32 v253, s7, 9
	s_movk_i32 s85, 0x90
	s_movk_i32 s6, 0x4400
	s_movk_i32 s7, 0x110
	s_movk_i32 s8, 0xf7
	s_movk_i32 s9, 0x101
	s_mov_b32 s0, 0x3fd744fd
	s_lshl_b32 s27, s2, 1
	v_mbcnt_hi_u32_b32 v188, -1, v0
	v_writelane_b32 v254, s97, 57
	s_branch .LBB0_230

.LBB0_633:
	v_readlane_b32 s2, v254, 37
	v_readlane_b32 s3, v254, 38
	v_readlane_b32 s60, v255, 0
	s_and_b64 vcc, exec, s[2:3]
	v_readlane_b32 s97, v254, 57
	s_mov_b64 s[76:77], s[34:35]
	v_readlane_b32 s61, v255, 1
	s_cbranch_vccz .LBB0_641
	v_readlane_b32 s98, v253, 0
	v_readlane_b32 s99, v254, 32
	s_cmpk_eq_u32 s99, 0x100
	s_movk_i32 s99, 0x2000
	s_cselect_b32 s99, 0x1f00, s99
	s_cmpk_lt_u32 s98, 0x100
	s_cselect_b32 s98, 0x2000, s99
	v_readlane_b32 s2, v254, 60
	v_readlane_b32 s3, v254, 61
	s_lshl_b32 s2, s2, 25
	v_readlane_b32 s3, v254, 43
	v_readlane_b32 s38, v254, 33
	s_waitcnt lgkmcnt(0)
	v_readlane_b32 s99, v254, 32
	v_readlane_b32 s100, v254, 44
	v_and_b32_e32 v0, 63, v133
	v_lshrrev_b32_e32 v1, 6, v133
	v_mul_u32_u24_e32 v2, 0x4200, v1
	v_lshl_add_u32 v200, v0, 1, v2
	v_lshl_add_u32 v201, v0, 4, v2
	v_lshlrev_b32_e32 v3, 13, v1
	v_lshl_add_u32 v202, v0, 4, v3
	v_mov_b32_e32 v203, 0
	v_lshrrev_b32_e32 v4, 3, v133
	v_and_b32_e32 v4, 3, v4
	v_lshlrev_b32_e32 v4, 21, v4
	v_lshrrev_b32_e32 v5, 5, v133
	v_lshl_add_u32 v4, v5, 7, v4
	v_and_b32_e32 v5, 7, v133
	v_lshl_add_u32 v204, v5, 4, v4
	v_mov_b32_e32 v205, 0
	s_cmpk_gt_i32 s38, 0xfff
	s_cselect_b32 s42, s54, s52
	s_cselect_b32 s43, s55, s53
	s_mov_b32 s46, 0x2c00000
	s_cselect_b32 s46, 0xac00000, s46
	s_mov_b32 s44, 0x42800000
	s_cselect_b32 s44, 0x41500000, s44
	s_and_b32 s39, s3, 0x1ffe000
	s_or_b32 s80, s39, s2
	s_lshl_b32 s39, s80, 2
	s_add_u32 s42, s42, s39
	s_addc_u32 s43, s43, 0
	v_lshl_add_u64 v[0:1], s[42:43], 0, v[202:203]
	s_add_u32 s42, s42, 0x1000
	s_addc_u32 s43, s43, 0
	v_lshl_add_u64 v[2:3], s[42:43], 0, v[202:203]
	global_load_dwordx4 v[142:145], v[0:1], off
	global_load_dwordx4 v[146:149], v[0:1], off offset:1024
	global_load_dwordx4 v[150:153], v[0:1], off offset:2048
	global_load_dwordx4 v[154:157], v[0:1], off offset:3072
	global_load_dwordx4 v[158:161], v[2:3], off
	global_load_dwordx4 v[162:165], v[2:3], off offset:1024
	global_load_dwordx4 v[166:169], v[2:3], off offset:2048
	global_load_dwordx4 v[170:173], v[2:3], off offset:3072
	s_lshr_b32 s39, s80, 1
	s_and_b32 s39, s39, 0x3800000
	s_lshr_b32 s47, s80, 3
	s_and_b32 s47, s47, 0x1fff80
	s_or_b32 s39, s39, s47
	s_add_u32 s46, s46, s39
	s_add_u32 s46, s58, s46
	s_addc_u32 s47, s59, 0
	v_lshl_add_u64 v[240:241], s[46:47], 0, v[204:205]
	v_mov_b32_e32 v8, s44
